# last 800 Hyena filter items moved out of phase 1 into the idle time of GEMM<0>'s partial last tile round (224 idle workgroups)
# speedup vs baseline: 1.0065x; 1.0065x over previous
.LBB0_1306:
	s_cmpk_lt_u32 s14, 0x20
	s_cbranch_scc1 .Lp2f_skip
	s_add_u32 s2, s14, 0x4e0
	s_nop 0
	v_writelane_b32 v255, s2, 59
	s_movk_i32 s2, 0xe0
	s_nop 0
	v_writelane_b32 v255, s2, 60
	s_movk_i32 s2, 0x81f
	s_nop 0
	v_writelane_b32 v255, s2, 58
	s_mov_b32 s2, 3
	s_nop 0
	v_writelane_b32 v255, s2, 61
	s_mov_b64 s[0:1], 0
	s_branch .LBB0_1319
.Lp2f_back:
.Lp2f_skip:
	s_mov_b64 s[0:1], 0

.Lp1sw_filter:
	v_readlane_b32 s2, v255, 61
	s_nop 1
	s_cmp_eq_u32 s2, 3
	s_cbranch_scc1 .Lflt_params
	v_readlane_b32 s2, v253, 36
	s_nop 1
	v_writelane_b32 v255, s2, 59
	s_movk_i32 s2, 0x100
	s_nop 0
	v_writelane_b32 v255, s2, 60
	s_movk_i32 s2, 0x4ff
	s_nop 0
	v_writelane_b32 v255, s2, 58
.Lflt_params:
	v_mov_b32_e32 v42, v179
	s_and_b64 vcc, exec, s[0:1]
	s_cbranch_vccnz .LBB0_1335
	s_movk_i32 s0, 0x800
	v_and_b32_e32 v43, 31, v42
	v_cmp_gt_i32_e64 s[52:53], s0, v42
	v_ashrrev_i32_e32 v0, 2, v42
	s_movk_i32 s0, 0x104
	v_and_b32_e32 v44, -8, v0
	v_and_b32_e32 v0, 0xffffffe0, v42
	v_mad_u32_u24 v45, v43, s0, 32
	s_add_i32 s0, 32, 0x8200
	v_add_u32_e32 v47, s0, v0
	v_readlane_b32 s0, v253, 36
	v_lshlrev_b32_e32 v46, 2, v42
	v_readlane_b32 s8, v255, 59
	v_readlane_b32 s1, v253, 37
	v_readfirstlane_b32 s2, v42
	s_cmp_ge_u32 s2, 0x100
	s_cbranch_scc0 .Lp1_np
	s_setprio 1

.LBB0_1332:
	s_waitcnt lgkmcnt(0)
	s_barrier
	ds_read_b32 v160, v158 offset:0
	ds_read_b32 v161, v158 offset:128
	ds_read_b32 v162, v159
	ds_read_b32 v163, v158 offset:1024
	ds_read_b32 v164, v158 offset:1152
	ds_read_b32 v165, v159 offset:8
	ds_read_b32 v166, v158 offset:2048
	ds_read_b32 v167, v158 offset:2176
	ds_read_b32 v168, v159 offset:16
	ds_read_b32 v169, v158 offset:3072
	ds_read_b32 v170, v158 offset:3200
	ds_read_b32 v171, v159 offset:24
	s_waitcnt vmcnt(0)
	s_waitcnt lgkmcnt(9)
	v_mfma_f32_32x32x2_f32 v[124:139], v160, v162, v[124:139]
	v_mfma_f32_32x32x2_f32 v[140:155], v161, v162, v[140:155]
	ds_read_b32 v160, v158 offset:4096
	ds_read_b32 v161, v158 offset:4224
	ds_read_b32 v162, v159 offset:32
	s_waitcnt lgkmcnt(9)
	v_mfma_f32_32x32x2_f32 v[124:139], v163, v165, v[124:139]
	v_mfma_f32_32x32x2_f32 v[140:155], v164, v165, v[140:155]
	ds_read_b32 v163, v158 offset:5120
	ds_read_b32 v164, v158 offset:5248
	ds_read_b32 v165, v159 offset:40
	s_waitcnt lgkmcnt(9)
	v_mfma_f32_32x32x2_f32 v[124:139], v166, v168, v[124:139]
	v_mfma_f32_32x32x2_f32 v[140:155], v167, v168, v[140:155]
	ds_read_b32 v166, v158 offset:6144
	ds_read_b32 v167, v158 offset:6272
	ds_read_b32 v168, v159 offset:48
	s_waitcnt lgkmcnt(9)
	v_mfma_f32_32x32x2_f32 v[124:139], v169, v171, v[124:139]
	v_mfma_f32_32x32x2_f32 v[140:155], v170, v171, v[140:155]
	ds_read_b32 v169, v158 offset:7168
	ds_read_b32 v170, v158 offset:7296
	ds_read_b32 v171, v159 offset:56
	s_waitcnt lgkmcnt(9)
	v_mfma_f32_32x32x2_f32 v[124:139], v160, v162, v[124:139]
	v_mfma_f32_32x32x2_f32 v[140:155], v161, v162, v[140:155]
	ds_read_b32 v160, v158 offset:8192
	ds_read_b32 v161, v158 offset:8320
	ds_read_b32 v162, v159 offset:64
	s_waitcnt lgkmcnt(9)
	v_mfma_f32_32x32x2_f32 v[124:139], v163, v165, v[124:139]
	v_mfma_f32_32x32x2_f32 v[140:155], v164, v165, v[140:155]
	ds_read_b32 v163, v158 offset:9216
	ds_read_b32 v164, v158 offset:9344
	ds_read_b32 v165, v159 offset:72
	s_waitcnt lgkmcnt(9)
	v_mfma_f32_32x32x2_f32 v[124:139], v166, v168, v[124:139]
	v_mfma_f32_32x32x2_f32 v[140:155], v167, v168, v[140:155]
	ds_read_b32 v166, v158 offset:10240
	ds_read_b32 v167, v158 offset:10368
	ds_read_b32 v168, v159 offset:80
	s_waitcnt lgkmcnt(9)
	v_mfma_f32_32x32x2_f32 v[124:139], v169, v171, v[124:139]
	v_mfma_f32_32x32x2_f32 v[140:155], v170, v171, v[140:155]
	ds_read_b32 v169, v158 offset:11264
	ds_read_b32 v170, v158 offset:11392
	ds_read_b32 v171, v159 offset:88
	s_waitcnt lgkmcnt(9)
	v_mfma_f32_32x32x2_f32 v[124:139], v160, v162, v[124:139]
	v_mfma_f32_32x32x2_f32 v[140:155], v161, v162, v[140:155]
	ds_read_b32 v160, v158 offset:12288
	ds_read_b32 v161, v158 offset:12416
	ds_read_b32 v162, v159 offset:96
	s_waitcnt lgkmcnt(9)
	v_mfma_f32_32x32x2_f32 v[124:139], v163, v165, v[124:139]
	v_mfma_f32_32x32x2_f32 v[140:155], v164, v165, v[140:155]
	ds_read_b32 v163, v158 offset:13312
	ds_read_b32 v164, v158 offset:13440
	ds_read_b32 v165, v159 offset:104
	s_waitcnt lgkmcnt(9)
	v_mfma_f32_32x32x2_f32 v[124:139], v166, v168, v[124:139]
	v_mfma_f32_32x32x2_f32 v[140:155], v167, v168, v[140:155]
	ds_read_b32 v166, v158 offset:14336
	ds_read_b32 v167, v158 offset:14464
	ds_read_b32 v168, v159 offset:112
	s_waitcnt lgkmcnt(9)
	v_mfma_f32_32x32x2_f32 v[124:139], v169, v171, v[124:139]
	v_mfma_f32_32x32x2_f32 v[140:155], v170, v171, v[140:155]
	ds_read_b32 v169, v158 offset:15360
	ds_read_b32 v170, v158 offset:15488
	ds_read_b32 v171, v159 offset:120
	s_waitcnt lgkmcnt(9)
	v_mfma_f32_32x32x2_f32 v[124:139], v160, v162, v[124:139]
	v_mfma_f32_32x32x2_f32 v[140:155], v161, v162, v[140:155]
	ds_read_b32 v160, v158 offset:16384
	ds_read_b32 v161, v158 offset:16512
	ds_read_b32 v162, v159 offset:128
	s_waitcnt lgkmcnt(9)
	v_mfma_f32_32x32x2_f32 v[124:139], v163, v165, v[124:139]
	v_mfma_f32_32x32x2_f32 v[140:155], v164, v165, v[140:155]
	ds_read_b32 v163, v158 offset:17408
	ds_read_b32 v164, v158 offset:17536
	ds_read_b32 v165, v159 offset:136
	s_waitcnt lgkmcnt(9)
	v_mfma_f32_32x32x2_f32 v[124:139], v166, v168, v[124:139]
	v_mfma_f32_32x32x2_f32 v[140:155], v167, v168, v[140:155]
	ds_read_b32 v166, v158 offset:18432
	ds_read_b32 v167, v158 offset:18560
	ds_read_b32 v168, v159 offset:144
	s_waitcnt lgkmcnt(9)
	v_mfma_f32_32x32x2_f32 v[124:139], v169, v171, v[124:139]
	v_mfma_f32_32x32x2_f32 v[140:155], v170, v171, v[140:155]
	ds_read_b32 v169, v158 offset:19456
	ds_read_b32 v170, v158 offset:19584
	ds_read_b32 v171, v159 offset:152
	s_waitcnt lgkmcnt(9)
	v_mfma_f32_32x32x2_f32 v[124:139], v160, v162, v[124:139]
	v_mfma_f32_32x32x2_f32 v[140:155], v161, v162, v[140:155]
	ds_read_b32 v160, v158 offset:20480
	ds_read_b32 v161, v158 offset:20608
	ds_read_b32 v162, v159 offset:160
	s_waitcnt lgkmcnt(9)
	v_mfma_f32_32x32x2_f32 v[124:139], v163, v165, v[124:139]
	v_mfma_f32_32x32x2_f32 v[140:155], v164, v165, v[140:155]
	ds_read_b32 v163, v158 offset:21504
	ds_read_b32 v164, v158 offset:21632
	ds_read_b32 v165, v159 offset:168
	s_waitcnt lgkmcnt(9)
	v_mfma_f32_32x32x2_f32 v[124:139], v166, v168, v[124:139]
	v_mfma_f32_32x32x2_f32 v[140:155], v167, v168, v[140:155]
	ds_read_b32 v166, v158 offset:22528
	ds_read_b32 v167, v158 offset:22656
	ds_read_b32 v168, v159 offset:176
	s_waitcnt lgkmcnt(9)
	v_mfma_f32_32x32x2_f32 v[124:139], v169, v171, v[124:139]
	v_mfma_f32_32x32x2_f32 v[140:155], v170, v171, v[140:155]
	ds_read_b32 v169, v158 offset:23552
	ds_read_b32 v170, v158 offset:23680
	ds_read_b32 v171, v159 offset:184
	s_waitcnt lgkmcnt(9)
	v_mfma_f32_32x32x2_f32 v[124:139], v160, v162, v[124:139]
	v_mfma_f32_32x32x2_f32 v[140:155], v161, v162, v[140:155]
	ds_read_b32 v160, v158 offset:24576
	ds_read_b32 v161, v158 offset:24704
	ds_read_b32 v162, v159 offset:192
	s_waitcnt lgkmcnt(9)
	v_mfma_f32_32x32x2_f32 v[124:139], v163, v165, v[124:139]
	v_mfma_f32_32x32x2_f32 v[140:155], v164, v165, v[140:155]
	ds_read_b32 v163, v158 offset:25600
	ds_read_b32 v164, v158 offset:25728
	ds_read_b32 v165, v159 offset:200
	s_waitcnt lgkmcnt(9)
	v_mfma_f32_32x32x2_f32 v[124:139], v166, v168, v[124:139]
	v_mfma_f32_32x32x2_f32 v[140:155], v167, v168, v[140:155]
	ds_read_b32 v166, v158 offset:26624
	ds_read_b32 v167, v158 offset:26752
	ds_read_b32 v168, v159 offset:208
	s_waitcnt lgkmcnt(9)
	v_mfma_f32_32x32x2_f32 v[124:139], v169, v171, v[124:139]
	v_mfma_f32_32x32x2_f32 v[140:155], v170, v171, v[140:155]
	ds_read_b32 v169, v158 offset:27648
	ds_read_b32 v170, v158 offset:27776
	ds_read_b32 v171, v159 offset:216
	s_waitcnt lgkmcnt(9)
	v_mfma_f32_32x32x2_f32 v[124:139], v160, v162, v[124:139]
	v_mfma_f32_32x32x2_f32 v[140:155], v161, v162, v[140:155]
	ds_read_b32 v160, v158 offset:28672
	ds_read_b32 v161, v158 offset:28800
	ds_read_b32 v162, v159 offset:224
	s_waitcnt lgkmcnt(9)
	v_mfma_f32_32x32x2_f32 v[124:139], v163, v165, v[124:139]
	v_mfma_f32_32x32x2_f32 v[140:155], v164, v165, v[140:155]
	ds_read_b32 v163, v158 offset:29696
	ds_read_b32 v164, v158 offset:29824
	ds_read_b32 v165, v159 offset:232
	s_waitcnt lgkmcnt(9)
	v_mfma_f32_32x32x2_f32 v[124:139], v166, v168, v[124:139]
	v_mfma_f32_32x32x2_f32 v[140:155], v167, v168, v[140:155]
	ds_read_b32 v166, v158 offset:30720
	ds_read_b32 v167, v158 offset:30848
	ds_read_b32 v168, v159 offset:240
	s_waitcnt lgkmcnt(9)
	v_mfma_f32_32x32x2_f32 v[124:139], v169, v171, v[124:139]
	v_mfma_f32_32x32x2_f32 v[140:155], v170, v171, v[140:155]
	ds_read_b32 v169, v158 offset:31744
	ds_read_b32 v170, v158 offset:31872
	ds_read_b32 v171, v159 offset:248
	s_waitcnt lgkmcnt(9)
	v_mfma_f32_32x32x2_f32 v[124:139], v160, v162, v[124:139]
	v_mfma_f32_32x32x2_f32 v[140:155], v161, v162, v[140:155]
	s_waitcnt lgkmcnt(6)
	v_mfma_f32_32x32x2_f32 v[124:139], v163, v165, v[124:139]
	v_mfma_f32_32x32x2_f32 v[140:155], v164, v165, v[140:155]
	s_waitcnt lgkmcnt(3)
	v_mfma_f32_32x32x2_f32 v[124:139], v166, v168, v[124:139]
	v_mfma_f32_32x32x2_f32 v[140:155], v167, v168, v[140:155]
	s_waitcnt lgkmcnt(0)
	v_mfma_f32_32x32x2_f32 v[124:139], v169, v171, v[124:139]
	v_mfma_f32_32x32x2_f32 v[140:155], v170, v171, v[140:155]
	v_lshl_add_u32 v172, s10, 7, v156
	v_lshl_add_u32 v172, v109, 5, v172
	s_add_i32 s2, s9, -1
	v_cvt_f32_u32_e32 v54, s2
	v_cvt_f32_i32_e32 v11, v172
	v_mov_b32_e32 v60, 0xc0447cbd
	v_lshl_add_u32 v174, v108, 6, s11
	v_lshl_add_u32 v174, v157, 2, v174
	v_mad_i64_i32 v[176:177], s[2:3], s9, v174, 0
	v_lshl_add_u64 v[176:177], v[176:177], 2, s[0:1]
	v_mov_b32_e32 v180, v172
	v_mov_b32_e32 v181, v1
	v_lshl_add_u64 v[176:177], v[180:181], 2, v[176:177]
	v_div_scale_f32 v24, s[2:3], v54, v54, -v11
	v_rcp_f32_e32 v25, v24
	s_mov_b32 s4, 0x3fb8aa3b
	s_mov_b32 s5, 0xc2ce8ed0
	s_mov_b32 s6, 0x42b17218
	v_fma_f32 v39, -v24, v25, 1.0
	v_fmac_f32_e32 v25, v39, v25
	v_div_scale_f32 v39, vcc, -v11, v54, -v11
	v_mul_f32_e32 v56, v39, v25
	v_fma_f32 v57, -v24, v56, v39
	v_fmac_f32_e32 v56, v57, v25
	v_fma_f32 v24, -v24, v56, v39
	v_div_fmas_f32 v24, v24, v25, v56
	v_div_fixup_f32 v173, v24, v54, -v11
	s_lshl_b32 s14, s9, 2
	s_mov_b32 s15, 0
	s_mul_i32 s16, s14, 5
	s_mov_b32 s17, 0
	s_nop 7
	s_nop 7
	s_nop 3
	v_and_b32_e32 v24, 0x1ff, v174
	v_cvt_f32_u32_e32 v24, v24
	v_fmamk_f32 v55, v24, 0xbcc4df2d, v60
	v_mul_f32_e64 v24, |v55|, v173
	v_mul_f32_e32 v25, 0x3fb8aa3b, v24
	v_fma_f32 v39, v24, s4, -v25
	v_rndne_f32_e32 v56, v25
	v_fmac_f32_e32 v39, 0x32a5705f, v24
	v_sub_f32_e32 v25, v25, v56
	v_add_f32_e32 v25, v25, v39
	v_exp_f32_e32 v25, v25
	v_cvt_i32_f32_e32 v39, v56
	v_ldexp_f32 v25, v25, v39
	v_mul_f32_e32 v124, v25, v124
	global_store_dword v[176:177], v124, off
	v_add_u32_e32 v174, 1, v174
	v_lshl_add_u64 v[176:177], v[176:177], 0, s[14:15]
	v_and_b32_e32 v24, 0x1ff, v174
	v_cvt_f32_u32_e32 v24, v24
	v_fmamk_f32 v55, v24, 0xbcc4df2d, v60
	v_mul_f32_e64 v24, |v55|, v173
	v_mul_f32_e32 v25, 0x3fb8aa3b, v24
	v_fma_f32 v39, v24, s4, -v25
	v_rndne_f32_e32 v56, v25
	v_fmac_f32_e32 v39, 0x32a5705f, v24
	v_sub_f32_e32 v25, v25, v56
	v_add_f32_e32 v25, v25, v39
	v_exp_f32_e32 v25, v25
	v_cvt_i32_f32_e32 v39, v56
	v_ldexp_f32 v25, v25, v39
	v_mul_f32_e32 v125, v25, v125
	global_store_dword v[176:177], v125, off
	v_add_u32_e32 v174, 1, v174
	v_lshl_add_u64 v[176:177], v[176:177], 0, s[14:15]
	v_and_b32_e32 v24, 0x1ff, v174
	v_cvt_f32_u32_e32 v24, v24
	v_fmamk_f32 v55, v24, 0xbcc4df2d, v60
	v_mul_f32_e64 v24, |v55|, v173
	v_mul_f32_e32 v25, 0x3fb8aa3b, v24
	v_fma_f32 v39, v24, s4, -v25
	v_rndne_f32_e32 v56, v25
	v_fmac_f32_e32 v39, 0x32a5705f, v24
	v_sub_f32_e32 v25, v25, v56
	v_add_f32_e32 v25, v25, v39
	v_exp_f32_e32 v25, v25
	v_cvt_i32_f32_e32 v39, v56
	v_ldexp_f32 v25, v25, v39
	v_mul_f32_e32 v126, v25, v126
	global_store_dword v[176:177], v126, off
	v_add_u32_e32 v174, 1, v174
	v_lshl_add_u64 v[176:177], v[176:177], 0, s[14:15]
	v_and_b32_e32 v24, 0x1ff, v174
	v_cvt_f32_u32_e32 v24, v24
	v_fmamk_f32 v55, v24, 0xbcc4df2d, v60
	v_mul_f32_e64 v24, |v55|, v173
	v_mul_f32_e32 v25, 0x3fb8aa3b, v24
	v_fma_f32 v39, v24, s4, -v25
	v_rndne_f32_e32 v56, v25
	v_fmac_f32_e32 v39, 0x32a5705f, v24
	v_sub_f32_e32 v25, v25, v56
	v_add_f32_e32 v25, v25, v39
	v_exp_f32_e32 v25, v25
	v_cvt_i32_f32_e32 v39, v56
	v_ldexp_f32 v25, v25, v39
	v_mul_f32_e32 v127, v25, v127
	global_store_dword v[176:177], v127, off
	v_add_u32_e32 v174, 5, v174
	v_lshl_add_u64 v[176:177], v[176:177], 0, s[16:17]
	v_and_b32_e32 v24, 0x1ff, v174
	v_cvt_f32_u32_e32 v24, v24
	v_fmamk_f32 v55, v24, 0xbcc4df2d, v60
	v_mul_f32_e64 v24, |v55|, v173
	v_mul_f32_e32 v25, 0x3fb8aa3b, v24
	v_fma_f32 v39, v24, s4, -v25
	v_rndne_f32_e32 v56, v25
	v_fmac_f32_e32 v39, 0x32a5705f, v24
	v_sub_f32_e32 v25, v25, v56
	v_add_f32_e32 v25, v25, v39
	v_exp_f32_e32 v25, v25
	v_cvt_i32_f32_e32 v39, v56
	v_ldexp_f32 v25, v25, v39
	v_mul_f32_e32 v128, v25, v128
	global_store_dword v[176:177], v128, off
	v_add_u32_e32 v174, 1, v174
	v_lshl_add_u64 v[176:177], v[176:177], 0, s[14:15]
	v_and_b32_e32 v24, 0x1ff, v174
	v_cvt_f32_u32_e32 v24, v24
	v_fmamk_f32 v55, v24, 0xbcc4df2d, v60
	v_mul_f32_e64 v24, |v55|, v173
	v_mul_f32_e32 v25, 0x3fb8aa3b, v24
	v_fma_f32 v39, v24, s4, -v25
	v_rndne_f32_e32 v56, v25
	v_fmac_f32_e32 v39, 0x32a5705f, v24
	v_sub_f32_e32 v25, v25, v56
	v_add_f32_e32 v25, v25, v39
	v_exp_f32_e32 v25, v25
	v_cvt_i32_f32_e32 v39, v56
	v_ldexp_f32 v25, v25, v39
	v_mul_f32_e32 v129, v25, v129
	global_store_dword v[176:177], v129, off
	v_add_u32_e32 v174, 1, v174
	v_lshl_add_u64 v[176:177], v[176:177], 0, s[14:15]
	v_and_b32_e32 v24, 0x1ff, v174
	v_cvt_f32_u32_e32 v24, v24
	v_fmamk_f32 v55, v24, 0xbcc4df2d, v60
	v_mul_f32_e64 v24, |v55|, v173
	v_mul_f32_e32 v25, 0x3fb8aa3b, v24
	v_fma_f32 v39, v24, s4, -v25
	v_rndne_f32_e32 v56, v25
	v_fmac_f32_e32 v39, 0x32a5705f, v24
	v_sub_f32_e32 v25, v25, v56
	v_add_f32_e32 v25, v25, v39
	v_exp_f32_e32 v25, v25
	v_cvt_i32_f32_e32 v39, v56
	v_ldexp_f32 v25, v25, v39
	v_mul_f32_e32 v130, v25, v130
	global_store_dword v[176:177], v130, off
	v_add_u32_e32 v174, 1, v174
	v_lshl_add_u64 v[176:177], v[176:177], 0, s[14:15]
	v_and_b32_e32 v24, 0x1ff, v174
	v_cvt_f32_u32_e32 v24, v24
	v_fmamk_f32 v55, v24, 0xbcc4df2d, v60
	v_mul_f32_e64 v24, |v55|, v173
	v_mul_f32_e32 v25, 0x3fb8aa3b, v24
	v_fma_f32 v39, v24, s4, -v25
	v_rndne_f32_e32 v56, v25
	v_fmac_f32_e32 v39, 0x32a5705f, v24
	v_sub_f32_e32 v25, v25, v56
	v_add_f32_e32 v25, v25, v39
	v_exp_f32_e32 v25, v25
	v_cvt_i32_f32_e32 v39, v56
	v_ldexp_f32 v25, v25, v39
	v_mul_f32_e32 v131, v25, v131
	global_store_dword v[176:177], v131, off
	v_add_u32_e32 v174, 5, v174
	v_lshl_add_u64 v[176:177], v[176:177], 0, s[16:17]
	v_and_b32_e32 v24, 0x1ff, v174
	v_cvt_f32_u32_e32 v24, v24
	v_fmamk_f32 v55, v24, 0xbcc4df2d, v60
	v_mul_f32_e64 v24, |v55|, v173
	v_mul_f32_e32 v25, 0x3fb8aa3b, v24
	v_fma_f32 v39, v24, s4, -v25
	v_rndne_f32_e32 v56, v25
	v_fmac_f32_e32 v39, 0x32a5705f, v24
	v_sub_f32_e32 v25, v25, v56
	v_add_f32_e32 v25, v25, v39
	v_exp_f32_e32 v25, v25
	v_cvt_i32_f32_e32 v39, v56
	v_ldexp_f32 v25, v25, v39
	v_mul_f32_e32 v132, v25, v132
	global_store_dword v[176:177], v132, off
	v_add_u32_e32 v174, 1, v174
	v_lshl_add_u64 v[176:177], v[176:177], 0, s[14:15]
	v_and_b32_e32 v24, 0x1ff, v174
	v_cvt_f32_u32_e32 v24, v24
	v_fmamk_f32 v55, v24, 0xbcc4df2d, v60
	v_mul_f32_e64 v24, |v55|, v173
	v_mul_f32_e32 v25, 0x3fb8aa3b, v24
	v_fma_f32 v39, v24, s4, -v25
	v_rndne_f32_e32 v56, v25
	v_fmac_f32_e32 v39, 0x32a5705f, v24
	v_sub_f32_e32 v25, v25, v56
	v_add_f32_e32 v25, v25, v39
	v_exp_f32_e32 v25, v25
	v_cvt_i32_f32_e32 v39, v56
	v_ldexp_f32 v25, v25, v39
	v_mul_f32_e32 v133, v25, v133
	global_store_dword v[176:177], v133, off
	v_add_u32_e32 v174, 1, v174
	v_lshl_add_u64 v[176:177], v[176:177], 0, s[14:15]
	v_and_b32_e32 v24, 0x1ff, v174
	v_cvt_f32_u32_e32 v24, v24
	v_fmamk_f32 v55, v24, 0xbcc4df2d, v60
	v_mul_f32_e64 v24, |v55|, v173
	v_mul_f32_e32 v25, 0x3fb8aa3b, v24
	v_fma_f32 v39, v24, s4, -v25
	v_rndne_f32_e32 v56, v25
	v_fmac_f32_e32 v39, 0x32a5705f, v24
	v_sub_f32_e32 v25, v25, v56
	v_add_f32_e32 v25, v25, v39
	v_exp_f32_e32 v25, v25
	v_cvt_i32_f32_e32 v39, v56
	v_ldexp_f32 v25, v25, v39
	v_mul_f32_e32 v134, v25, v134
	global_store_dword v[176:177], v134, off
	v_add_u32_e32 v174, 1, v174
	v_lshl_add_u64 v[176:177], v[176:177], 0, s[14:15]
	v_and_b32_e32 v24, 0x1ff, v174
	v_cvt_f32_u32_e32 v24, v24
	v_fmamk_f32 v55, v24, 0xbcc4df2d, v60
	v_mul_f32_e64 v24, |v55|, v173
	v_mul_f32_e32 v25, 0x3fb8aa3b, v24
	v_fma_f32 v39, v24, s4, -v25
	v_rndne_f32_e32 v56, v25
	v_fmac_f32_e32 v39, 0x32a5705f, v24
	v_sub_f32_e32 v25, v25, v56
	v_add_f32_e32 v25, v25, v39
	v_exp_f32_e32 v25, v25
	v_cvt_i32_f32_e32 v39, v56
	v_ldexp_f32 v25, v25, v39
	v_mul_f32_e32 v135, v25, v135
	global_store_dword v[176:177], v135, off
	v_add_u32_e32 v174, 5, v174
	v_lshl_add_u64 v[176:177], v[176:177], 0, s[16:17]
	v_and_b32_e32 v24, 0x1ff, v174
	v_cvt_f32_u32_e32 v24, v24
	v_fmamk_f32 v55, v24, 0xbcc4df2d, v60
	v_mul_f32_e64 v24, |v55|, v173
	v_mul_f32_e32 v25, 0x3fb8aa3b, v24
	v_fma_f32 v39, v24, s4, -v25
	v_rndne_f32_e32 v56, v25
	v_fmac_f32_e32 v39, 0x32a5705f, v24
	v_sub_f32_e32 v25, v25, v56
	v_add_f32_e32 v25, v25, v39
	v_exp_f32_e32 v25, v25
	v_cvt_i32_f32_e32 v39, v56
	v_ldexp_f32 v25, v25, v39
	v_mul_f32_e32 v136, v25, v136
	global_store_dword v[176:177], v136, off
	v_add_u32_e32 v174, 1, v174
	v_lshl_add_u64 v[176:177], v[176:177], 0, s[14:15]
	v_and_b32_e32 v24, 0x1ff, v174
	v_cvt_f32_u32_e32 v24, v24
	v_fmamk_f32 v55, v24, 0xbcc4df2d, v60
	v_mul_f32_e64 v24, |v55|, v173
	v_mul_f32_e32 v25, 0x3fb8aa3b, v24
	v_fma_f32 v39, v24, s4, -v25
	v_rndne_f32_e32 v56, v25
	v_fmac_f32_e32 v39, 0x32a5705f, v24
	v_sub_f32_e32 v25, v25, v56
	v_add_f32_e32 v25, v25, v39
	v_exp_f32_e32 v25, v25
	v_cvt_i32_f32_e32 v39, v56
	v_ldexp_f32 v25, v25, v39
	v_mul_f32_e32 v137, v25, v137
	global_store_dword v[176:177], v137, off
	v_add_u32_e32 v174, 1, v174
	v_lshl_add_u64 v[176:177], v[176:177], 0, s[14:15]
	v_and_b32_e32 v24, 0x1ff, v174
	v_cvt_f32_u32_e32 v24, v24
	v_fmamk_f32 v55, v24, 0xbcc4df2d, v60
	v_mul_f32_e64 v24, |v55|, v173
	v_mul_f32_e32 v25, 0x3fb8aa3b, v24
	v_fma_f32 v39, v24, s4, -v25
	v_rndne_f32_e32 v56, v25
	v_fmac_f32_e32 v39, 0x32a5705f, v24
	v_sub_f32_e32 v25, v25, v56
	v_add_f32_e32 v25, v25, v39
	v_exp_f32_e32 v25, v25
	v_cvt_i32_f32_e32 v39, v56
	v_ldexp_f32 v25, v25, v39
	v_mul_f32_e32 v138, v25, v138
	global_store_dword v[176:177], v138, off
	v_add_u32_e32 v174, 1, v174
	v_lshl_add_u64 v[176:177], v[176:177], 0, s[14:15]
	v_and_b32_e32 v24, 0x1ff, v174
	v_cvt_f32_u32_e32 v24, v24
	v_fmamk_f32 v55, v24, 0xbcc4df2d, v60
	v_mul_f32_e64 v24, |v55|, v173
	v_mul_f32_e32 v25, 0x3fb8aa3b, v24
	v_fma_f32 v39, v24, s4, -v25
	v_rndne_f32_e32 v56, v25
	v_fmac_f32_e32 v39, 0x32a5705f, v24
	v_sub_f32_e32 v25, v25, v56
	v_add_f32_e32 v25, v25, v39
	v_exp_f32_e32 v25, v25
	v_cvt_i32_f32_e32 v39, v56
	v_ldexp_f32 v25, v25, v39
	v_mul_f32_e32 v139, v25, v139
	global_store_dword v[176:177], v139, off
	v_add_u32_e32 v174, 5, v174
	v_lshl_add_u64 v[176:177], v[176:177], 0, s[16:17]
	v_and_b32_e32 v24, 0x1ff, v174
	v_cvt_f32_u32_e32 v24, v24
	v_fmamk_f32 v55, v24, 0xbcc4df2d, v60
	v_mul_f32_e64 v24, |v55|, v173
	v_mul_f32_e32 v25, 0x3fb8aa3b, v24
	v_fma_f32 v39, v24, s4, -v25
	v_rndne_f32_e32 v56, v25
	v_fmac_f32_e32 v39, 0x32a5705f, v24
	v_sub_f32_e32 v25, v25, v56
	v_add_f32_e32 v25, v25, v39
	v_exp_f32_e32 v25, v25
	v_cvt_i32_f32_e32 v39, v56
	v_ldexp_f32 v25, v25, v39
	v_mul_f32_e32 v140, v25, v140
	global_store_dword v[176:177], v140, off
	v_add_u32_e32 v174, 1, v174
	v_lshl_add_u64 v[176:177], v[176:177], 0, s[14:15]
	v_and_b32_e32 v24, 0x1ff, v174
	v_cvt_f32_u32_e32 v24, v24
	v_fmamk_f32 v55, v24, 0xbcc4df2d, v60
	v_mul_f32_e64 v24, |v55|, v173
	v_mul_f32_e32 v25, 0x3fb8aa3b, v24
	v_fma_f32 v39, v24, s4, -v25
	v_rndne_f32_e32 v56, v25
	v_fmac_f32_e32 v39, 0x32a5705f, v24
	v_sub_f32_e32 v25, v25, v56
	v_add_f32_e32 v25, v25, v39
	v_exp_f32_e32 v25, v25
	v_cvt_i32_f32_e32 v39, v56
	v_ldexp_f32 v25, v25, v39
	v_mul_f32_e32 v141, v25, v141
	global_store_dword v[176:177], v141, off
	v_add_u32_e32 v174, 1, v174
	v_lshl_add_u64 v[176:177], v[176:177], 0, s[14:15]
	v_and_b32_e32 v24, 0x1ff, v174
	v_cvt_f32_u32_e32 v24, v24
	v_fmamk_f32 v55, v24, 0xbcc4df2d, v60
	v_mul_f32_e64 v24, |v55|, v173
	v_mul_f32_e32 v25, 0x3fb8aa3b, v24
	v_fma_f32 v39, v24, s4, -v25
	v_rndne_f32_e32 v56, v25
	v_fmac_f32_e32 v39, 0x32a5705f, v24
	v_sub_f32_e32 v25, v25, v56
	v_add_f32_e32 v25, v25, v39
	v_exp_f32_e32 v25, v25
	v_cvt_i32_f32_e32 v39, v56
	v_ldexp_f32 v25, v25, v39
	v_mul_f32_e32 v142, v25, v142
	global_store_dword v[176:177], v142, off
	v_add_u32_e32 v174, 1, v174
	v_lshl_add_u64 v[176:177], v[176:177], 0, s[14:15]
	v_and_b32_e32 v24, 0x1ff, v174
	v_cvt_f32_u32_e32 v24, v24
	v_fmamk_f32 v55, v24, 0xbcc4df2d, v60
	v_mul_f32_e64 v24, |v55|, v173
	v_mul_f32_e32 v25, 0x3fb8aa3b, v24
	v_fma_f32 v39, v24, s4, -v25
	v_rndne_f32_e32 v56, v25
	v_fmac_f32_e32 v39, 0x32a5705f, v24
	v_sub_f32_e32 v25, v25, v56
	v_add_f32_e32 v25, v25, v39
	v_exp_f32_e32 v25, v25
	v_cvt_i32_f32_e32 v39, v56
	v_ldexp_f32 v25, v25, v39
	v_mul_f32_e32 v143, v25, v143
	global_store_dword v[176:177], v143, off
	v_add_u32_e32 v174, 5, v174
	v_lshl_add_u64 v[176:177], v[176:177], 0, s[16:17]
	v_and_b32_e32 v24, 0x1ff, v174
	v_cvt_f32_u32_e32 v24, v24
	v_fmamk_f32 v55, v24, 0xbcc4df2d, v60
	v_mul_f32_e64 v24, |v55|, v173
	v_mul_f32_e32 v25, 0x3fb8aa3b, v24
	v_fma_f32 v39, v24, s4, -v25
	v_rndne_f32_e32 v56, v25
	v_fmac_f32_e32 v39, 0x32a5705f, v24
	v_sub_f32_e32 v25, v25, v56
	v_add_f32_e32 v25, v25, v39
	v_exp_f32_e32 v25, v25
	v_cvt_i32_f32_e32 v39, v56
	v_ldexp_f32 v25, v25, v39
	v_mul_f32_e32 v144, v25, v144
	global_store_dword v[176:177], v144, off
	v_add_u32_e32 v174, 1, v174
	v_lshl_add_u64 v[176:177], v[176:177], 0, s[14:15]
	v_and_b32_e32 v24, 0x1ff, v174
	v_cvt_f32_u32_e32 v24, v24
	v_fmamk_f32 v55, v24, 0xbcc4df2d, v60
	v_mul_f32_e64 v24, |v55|, v173
	v_mul_f32_e32 v25, 0x3fb8aa3b, v24
	v_fma_f32 v39, v24, s4, -v25
	v_rndne_f32_e32 v56, v25
	v_fmac_f32_e32 v39, 0x32a5705f, v24
	v_sub_f32_e32 v25, v25, v56
	v_add_f32_e32 v25, v25, v39
	v_exp_f32_e32 v25, v25
	v_cvt_i32_f32_e32 v39, v56
	v_ldexp_f32 v25, v25, v39
	v_mul_f32_e32 v145, v25, v145
	global_store_dword v[176:177], v145, off
	v_add_u32_e32 v174, 1, v174
	v_lshl_add_u64 v[176:177], v[176:177], 0, s[14:15]
	v_and_b32_e32 v24, 0x1ff, v174
	v_cvt_f32_u32_e32 v24, v24
	v_fmamk_f32 v55, v24, 0xbcc4df2d, v60
	v_mul_f32_e64 v24, |v55|, v173
	v_mul_f32_e32 v25, 0x3fb8aa3b, v24
	v_fma_f32 v39, v24, s4, -v25
	v_rndne_f32_e32 v56, v25
	v_fmac_f32_e32 v39, 0x32a5705f, v24
	v_sub_f32_e32 v25, v25, v56
	v_add_f32_e32 v25, v25, v39
	v_exp_f32_e32 v25, v25
	v_cvt_i32_f32_e32 v39, v56
	v_ldexp_f32 v25, v25, v39
	v_mul_f32_e32 v146, v25, v146
	global_store_dword v[176:177], v146, off
	v_add_u32_e32 v174, 1, v174
	v_lshl_add_u64 v[176:177], v[176:177], 0, s[14:15]
	v_and_b32_e32 v24, 0x1ff, v174
	v_cvt_f32_u32_e32 v24, v24
	v_fmamk_f32 v55, v24, 0xbcc4df2d, v60
	v_mul_f32_e64 v24, |v55|, v173
	v_mul_f32_e32 v25, 0x3fb8aa3b, v24
	v_fma_f32 v39, v24, s4, -v25
	v_rndne_f32_e32 v56, v25
	v_fmac_f32_e32 v39, 0x32a5705f, v24
	v_sub_f32_e32 v25, v25, v56
	v_add_f32_e32 v25, v25, v39
	v_exp_f32_e32 v25, v25
	v_cvt_i32_f32_e32 v39, v56
	v_ldexp_f32 v25, v25, v39
	v_mul_f32_e32 v147, v25, v147
	global_store_dword v[176:177], v147, off
	v_add_u32_e32 v174, 5, v174
	v_lshl_add_u64 v[176:177], v[176:177], 0, s[16:17]
	v_and_b32_e32 v24, 0x1ff, v174
	v_cvt_f32_u32_e32 v24, v24
	v_fmamk_f32 v55, v24, 0xbcc4df2d, v60
	v_mul_f32_e64 v24, |v55|, v173
	v_mul_f32_e32 v25, 0x3fb8aa3b, v24
	v_fma_f32 v39, v24, s4, -v25
	v_rndne_f32_e32 v56, v25
	v_fmac_f32_e32 v39, 0x32a5705f, v24
	v_sub_f32_e32 v25, v25, v56
	v_add_f32_e32 v25, v25, v39
	v_exp_f32_e32 v25, v25
	v_cvt_i32_f32_e32 v39, v56
	v_ldexp_f32 v25, v25, v39
	v_mul_f32_e32 v148, v25, v148
	global_store_dword v[176:177], v148, off
	v_add_u32_e32 v174, 1, v174
	v_lshl_add_u64 v[176:177], v[176:177], 0, s[14:15]
	v_and_b32_e32 v24, 0x1ff, v174
	v_cvt_f32_u32_e32 v24, v24
	v_fmamk_f32 v55, v24, 0xbcc4df2d, v60
	v_mul_f32_e64 v24, |v55|, v173
	v_mul_f32_e32 v25, 0x3fb8aa3b, v24
	v_fma_f32 v39, v24, s4, -v25
	v_rndne_f32_e32 v56, v25
	v_fmac_f32_e32 v39, 0x32a5705f, v24
	v_sub_f32_e32 v25, v25, v56
	v_add_f32_e32 v25, v25, v39
	v_exp_f32_e32 v25, v25
	v_cvt_i32_f32_e32 v39, v56
	v_ldexp_f32 v25, v25, v39
	v_mul_f32_e32 v149, v25, v149
	global_store_dword v[176:177], v149, off
	v_add_u32_e32 v174, 1, v174
	v_lshl_add_u64 v[176:177], v[176:177], 0, s[14:15]
	v_and_b32_e32 v24, 0x1ff, v174
	v_cvt_f32_u32_e32 v24, v24
	v_fmamk_f32 v55, v24, 0xbcc4df2d, v60
	v_mul_f32_e64 v24, |v55|, v173
	v_mul_f32_e32 v25, 0x3fb8aa3b, v24
	v_fma_f32 v39, v24, s4, -v25
	v_rndne_f32_e32 v56, v25
	v_fmac_f32_e32 v39, 0x32a5705f, v24
	v_sub_f32_e32 v25, v25, v56
	v_add_f32_e32 v25, v25, v39
	v_exp_f32_e32 v25, v25
	v_cvt_i32_f32_e32 v39, v56
	v_ldexp_f32 v25, v25, v39
	v_mul_f32_e32 v150, v25, v150
	global_store_dword v[176:177], v150, off
	v_add_u32_e32 v174, 1, v174
	v_lshl_add_u64 v[176:177], v[176:177], 0, s[14:15]
	v_and_b32_e32 v24, 0x1ff, v174
	v_cvt_f32_u32_e32 v24, v24
	v_fmamk_f32 v55, v24, 0xbcc4df2d, v60
	v_mul_f32_e64 v24, |v55|, v173
	v_mul_f32_e32 v25, 0x3fb8aa3b, v24
	v_fma_f32 v39, v24, s4, -v25
	v_rndne_f32_e32 v56, v25
	v_fmac_f32_e32 v39, 0x32a5705f, v24
	v_sub_f32_e32 v25, v25, v56
	v_add_f32_e32 v25, v25, v39
	v_exp_f32_e32 v25, v25
	v_cvt_i32_f32_e32 v39, v56
	v_ldexp_f32 v25, v25, v39
	v_mul_f32_e32 v151, v25, v151
	global_store_dword v[176:177], v151, off
	v_add_u32_e32 v174, 5, v174
	v_lshl_add_u64 v[176:177], v[176:177], 0, s[16:17]
	v_and_b32_e32 v24, 0x1ff, v174
	v_cvt_f32_u32_e32 v24, v24
	v_fmamk_f32 v55, v24, 0xbcc4df2d, v60
	v_mul_f32_e64 v24, |v55|, v173
	v_mul_f32_e32 v25, 0x3fb8aa3b, v24
	v_fma_f32 v39, v24, s4, -v25
	v_rndne_f32_e32 v56, v25
	v_fmac_f32_e32 v39, 0x32a5705f, v24
	v_sub_f32_e32 v25, v25, v56
	v_add_f32_e32 v25, v25, v39
	v_exp_f32_e32 v25, v25
	v_cvt_i32_f32_e32 v39, v56
	v_ldexp_f32 v25, v25, v39
	v_mul_f32_e32 v152, v25, v152
	global_store_dword v[176:177], v152, off
	v_add_u32_e32 v174, 1, v174
	v_lshl_add_u64 v[176:177], v[176:177], 0, s[14:15]
	v_and_b32_e32 v24, 0x1ff, v174
	v_cvt_f32_u32_e32 v24, v24
	v_fmamk_f32 v55, v24, 0xbcc4df2d, v60
	v_mul_f32_e64 v24, |v55|, v173
	v_mul_f32_e32 v25, 0x3fb8aa3b, v24
	v_fma_f32 v39, v24, s4, -v25
	v_rndne_f32_e32 v56, v25
	v_fmac_f32_e32 v39, 0x32a5705f, v24
	v_sub_f32_e32 v25, v25, v56
	v_add_f32_e32 v25, v25, v39
	v_exp_f32_e32 v25, v25
	v_cvt_i32_f32_e32 v39, v56
	v_ldexp_f32 v25, v25, v39
	v_mul_f32_e32 v153, v25, v153
	global_store_dword v[176:177], v153, off
	v_add_u32_e32 v174, 1, v174
	v_lshl_add_u64 v[176:177], v[176:177], 0, s[14:15]
	v_and_b32_e32 v24, 0x1ff, v174
	v_cvt_f32_u32_e32 v24, v24
	v_fmamk_f32 v55, v24, 0xbcc4df2d, v60
	v_mul_f32_e64 v24, |v55|, v173
	v_mul_f32_e32 v25, 0x3fb8aa3b, v24
	v_fma_f32 v39, v24, s4, -v25
	v_rndne_f32_e32 v56, v25
	v_fmac_f32_e32 v39, 0x32a5705f, v24
	v_sub_f32_e32 v25, v25, v56
	v_add_f32_e32 v25, v25, v39
	v_exp_f32_e32 v25, v25
	v_cvt_i32_f32_e32 v39, v56
	v_ldexp_f32 v25, v25, v39
	v_mul_f32_e32 v154, v25, v154
	global_store_dword v[176:177], v154, off
	v_add_u32_e32 v174, 1, v174
	v_lshl_add_u64 v[176:177], v[176:177], 0, s[14:15]
	v_and_b32_e32 v24, 0x1ff, v174
	v_cvt_f32_u32_e32 v24, v24
	v_fmamk_f32 v55, v24, 0xbcc4df2d, v60
	v_mul_f32_e64 v24, |v55|, v173
	v_mul_f32_e32 v25, 0x3fb8aa3b, v24
	v_fma_f32 v39, v24, s4, -v25
	v_rndne_f32_e32 v56, v25
	v_fmac_f32_e32 v39, 0x32a5705f, v24
	v_sub_f32_e32 v25, v25, v56
	v_add_f32_e32 v25, v25, v39
	v_exp_f32_e32 v25, v25
	v_cvt_i32_f32_e32 v39, v56
	v_ldexp_f32 v25, v25, v39
	v_mul_f32_e32 v155, v25, v155
	global_store_dword v[176:177], v155, off
	v_readlane_b32 s12, v254, 39
	v_readlane_b32 s13, v254, 40
	v_readlane_b32 s14, v254, 41
	v_readlane_b32 s15, v254, 42
	v_readlane_b32 s16, v254, 43
	v_readlane_b32 s17, v254, 44
	v_readlane_b32 s18, v254, 45
	v_readlane_b32 s19, v254, 46
	v_readlane_b32 s20, v254, 47
	v_readlane_b32 s21, v254, 48
	v_readlane_b32 s22, v254, 49
	v_readlane_b32 s23, v254, 50
	v_readlane_b32 s24, v254, 51
	v_readlane_b32 s25, v254, 52
	v_readlane_b32 s26, v254, 53
	v_readlane_b32 s27, v254, 54
	v_readlane_b32 s0, v251, 20
	v_readlane_b32 s1, v251, 21
	s_nop 4
	v_readlane_b32 s0, v255, 60
	v_readlane_b32 s1, v255, 58
	s_nop 0
	s_add_i32 s8, s8, s0
	s_cmp_gt_i32 s8, s1
	s_cbranch_scc0 .LBB0_1321
.LBB0_1335:
	s_setprio 0
	v_readlane_b32 s2, v255, 61
	s_nop 1
	s_cmp_eq_u32 s2, 3
	s_cbranch_scc0 .Lp2f_noret
	s_mov_b32 s2, 0
	s_nop 0
	v_writelane_b32 v255, s2, 61
	s_branch .Lp2f_back
.Lp2f_noret:
	v_readlane_b32 s2, v255, 61
	s_nop 1
	s_cmp_eq_u32 s2, 1
	s_cbranch_scc0 .Lp1sw_done
	s_mov_b32 s2, 2
	s_nop 0
	v_writelane_b32 v255, s2, 61
	s_branch .Lp1sw_normal
